# v89 with the grid-barrier poll spacing halved (s_sleep 10 -> 5 between the two in-flight polls)
# baseline (speedup 1.0000x reference)
.Lgb0_spin:
	global_load_dword v1, v5, s[10:11] sc1
	s_sleep 5
	global_load_dword v3, v5, s[10:11] sc1
.Lgb0_spin2:
	s_waitcnt vmcnt(1)
	v_readfirstlane_b32 s9, v1
	s_sub_i32 s9, s9, s8
	s_cmp_ge_i32 s9, 0
	s_cbranch_scc1 .Lgb0_done
	s_sleep 5
	global_load_dword v1, v5, s[10:11] sc1
	s_waitcnt vmcnt(1)
	v_readfirstlane_b32 s9, v3
	s_sub_i32 s9, s9, s8
	s_cmp_ge_i32 s9, 0
	s_cbranch_scc1 .Lgb0_done
	s_sleep 5
	global_load_dword v3, v5, s[10:11] sc1
	s_add_i32 s12, s12, 1
	s_cmp_lt_u32 s12, 0x40000
	s_cbranch_scc1 .Lgb0_spin2

.LBB0_1053:
	s_waitcnt lgkmcnt(0)
	s_and_b32 s0, s91, 7
	s_lshl_b32 s0, s0, 3
	s_bfe_u32 s1, s91, 0x30003
	s_add_i32 s0, s0, s1
	v_readlane_b32 s1, v255, 45
	s_lshl_b32 s1, s1, 6
	s_add_i32 s0, s0, s1
	s_lshl_b32 s0, s0, 2
	s_add_i32 s0, s0, 14080
	v_readlane_b32 s2, v251, 32
	v_readlane_b32 s3, v251, 33
	s_add_u32 s2, s2, s0
	s_addc_u32 s3, s3, 0
	s_mov_b32 s12, 0
	v_mov_b32_e32 v5, 0
	global_load_dword v1, v5, s[2:3] sc1
	s_sleep 5
.Lgb7_spin:
	global_load_dword v3, v5, s[2:3] sc1
	s_waitcnt vmcnt(1)
	v_readfirstlane_b32 s9, v1
	s_cmp_ge_u32 s9, 4
	s_cbranch_scc1 .Lgb7_done
	s_sleep 5
	global_load_dword v1, v5, s[2:3] sc1
	s_waitcnt vmcnt(1)
	v_readfirstlane_b32 s9, v3
	s_cmp_ge_u32 s9, 4
	s_cbranch_scc1 .Lgb7_done
	s_sleep 5
	s_add_i32 s12, s12, 1
	s_cmp_lt_u32 s12, 0x80000
	s_cbranch_scc1 .Lgb7_spin
